# v20_qfast
# speedup vs baseline: 1.0076x; 1.0065x over previous
; DI int next_item(u32* ctr0, int idx, int* sh) {
;   asm volatile("" : "+s"(idx));
;   u32* ctr = ctr0 + idx;
;   __syncthreads();
;   if (threadIdx.x == 0) *sh = (int)atomicAdd(ctr, 1u);
;   __syncthreads();
;   return *sh;
; }
; __global__ void __launch_bounds__(NT) fwd_megakernel(Params p) {
;     ...
;       case 5: {
;         for (;;) {
;           const int it = next_item(p.ctr, layer * 8 + 2, &sh_item);
;           if (it >= 512) break;
.LBB0_144:
	s_cmp_gt_i32 s61, 4
	s_mov_b64 s[0:1], -1
	s_cbranch_scc0 .LBB0_187
	v_readlane_b32 s0, v250, 28
	s_lshl_b32 s0, s0, 3
	s_or_b32 s8, s0, 2
	v_readlane_b32 s1, v250, 29
	s_branch .Lq_first_0
.Lq_first_0:
	s_mov_b32 s0, s8
	s_waitcnt vmcnt(0) lgkmcnt(0)
	s_barrier
	s_mov_b64 s[4:5], exec
	v_readlane_b32 s6, v248, 2
	v_readlane_b32 s7, v248, 3
	s_and_b64 s[6:7], s[4:5], s[6:7]
	s_mov_b64 exec, s[6:7]
	s_cbranch_execz .LBB0_151
	s_ashr_i32 s1, s0, 31
	v_lshl_add_u64 v[2:3], s[0:1], 2, v[190:191]
	global_atomic_add v0, v[2:3], v209, off sc0
	s_waitcnt vmcnt(0)
	ds_write_b32 v1, v0 offset:48
.LBB0_151:
	s_or_b64 exec, exec, s[4:5]
	s_waitcnt lgkmcnt(0)
	s_barrier
	s_branch .Lq_common_0

; DI int opq(int x) { asm volatile("" : "+v"(x)); return x; }
; DI f32x16 zero16() { f32x16 z; for (int i = 0; i < 16; ++i) z[i] = 0.f; return z; }
; DI long vt_off(int grp, int b, int head) { return ((long)((grp * BATCH + b) * 4 + head)) * 128 * SEQ; }
; DI int pi32(int r) { return (r & 0x13) | ((r & 4) << 1) | ((r & 8) >> 1); }
; template <int DQK, int MODE>
; DI void attn_core(const u16* __restrict__ Qg, int ldq, const u16* __restrict__ Kg, int ldk, const u16* __restrict__ Vtg,
;                   const u64* __restrict__ maskg, int q0, float scale, char* smem, int* sflags, f32x16 (&o)[4], float& l_run) {
;     ...
;   const int tid = opq(threadIdx.x), lane = tid & 63, wid = tid >> 6, l31 = lane & 31, hh = lane >> 5;
;   const int qrow = q0 + 32 * wid + l31;
;   bf16x8 qf[NKS];
; #pragma unroll
;   for (int ks = 0; ks < NKS; ++ks) qf[ks] = *(const bf16x8*)(Qg + (long)qrow * ldq + ks * 16 + hh * 8);
;   o[0] = zero16(); o[1] = zero16(); o[2] = zero16(); o[3] = zero16();
;   float m_run = -1e30f, r_run = 0.f;
;   l_run = 0.f;
;   const int ntiles = (q0 + 256) >> 6;
;   const int step = (MODE == 2) ? -1 : 1;
;   int tau = (MODE == 2) ? ntiles - 1 : 0;
;   u32x4 rk[NVK], rv[2];
;   auto gload = [&](int tt) {
; #pragma unroll
;     for (int i = 0; i < NVK; ++i) {
;       const int v = tid + NT * i, row = v / VPR, c = v % VPR;
;       rk[i] = *(const u32x4*)(Kg + (long)(tt * 64 + row) * ldk + c * 8);
;     }
; #pragma unroll
;     for (int i = 0; i < 2; ++i) {
;       const int v = tid + NT * i, row = v >> 3, c = v & 7;
;       rv[i] = *(const u32x4*)(Vtg + (long)row * SEQ + tt * 64 + c * 8);
;     }
;   };
;   if (MODE != 2) gload(tau);
;   const float sc = scale * LOG2E;
;   const int krow = pi32(l31);
; __global__ void __launch_bounds__(NT) fwd_megakernel(Params p) {
;     ...
;           const int it = next_item(p.ctr, layer * 8 + 2, &sh_item);
;           if (it >= 512) break;
;           const int t = it >> 1;
;           const int qt = 15 - (t >> 4), bh = t & 15, b = bh >> 2, head = bh & 3;
;           if (it & 1) {
;             const u16* base = p.PROJ + (long)b * SEQ * PW;
;     ...
;             attn_item_simple<128, 1>(p, base + DQ + head * 128, PW, base + DK + head * 128, PW, p.VT + vt_off(3, b, head),
;                                      p.MASK + (long)b * SEQ * 64, b, qt * 256, 0.08838834764831845f, 1536 + head * 128, smem, sflags);
.LBB0_149:
	s_mov_b32 s0, s8
	s_mov_b64 s[4:5], exec
	v_readlane_b32 s6, v248, 2
	v_readlane_b32 s7, v248, 3
	s_and_b64 s[6:7], s[4:5], s[6:7]
	s_mov_b64 exec, s[6:7]
	s_cbranch_execz .Lq_skip_0
	s_ashr_i32 s1, s0, 31
	v_lshl_add_u64 v[2:3], s[0:1], 2, v[190:191]
	global_atomic_add v0, v[2:3], v209, off sc0
	s_waitcnt vmcnt(0)
	ds_write_b32 v1, v0 offset:48
.Lq_skip_0:
	s_or_b64 exec, exec, s[4:5]
	s_waitcnt vmcnt(0) lgkmcnt(0)
	s_barrier
.Lq_common_0:
	ds_read_b32 v0, v1 offset:48
	s_movk_i32 s0, 0x1ff
	s_waitcnt lgkmcnt(0)
	v_cmp_lt_i32_e32 vcc, s0, v0
	v_readfirstlane_b32 s4, v0
	s_mov_b64 s[0:1], -1
	s_cbranch_vccnz .LBB0_148
	s_ashr_i32 s0, s4, 5
	s_sub_i32 s6, 15, s0
	s_bfe_u32 s10, s4, 0x20003
	s_bfe_u32 s9, s4, 0x20001
	s_bitcmp0_b32 s4, 0
	s_mov_b64 s[0:1], -1
	s_cbranch_scc1 .LBB0_167
	s_lshl_b32 s11, s10, 12
	s_mul_i32 s0, s10, 0x2600000
	v_readlane_b32 s16, v249, 6
	v_readlane_b32 s17, v249, 7
	s_add_u32 s0, s16, s0
	s_addc_u32 s1, s17, 0
	s_lshl_b32 s7, s9, 7
	s_lshl_b32 s4, s9, 8
	s_add_u32 s0, s0, s4
	s_addc_u32 s1, s1, 0
	s_add_u32 s14, s0, 0x1000
	s_addc_u32 s15, s1, 0
	s_add_u32 s0, s0, 0x1400
	s_addc_u32 s1, s1, 0
	s_lshl_b32 s5, s10, 22
	s_lshl_b32 s12, s9, 20
	v_readlane_b32 s18, v249, 8
	s_lshl_b32 s4, s10, 21
	s_or_b32 s5, s12, s5
	v_readlane_b32 s19, v249, 9
	v_readlane_b32 s20, v249, 10
	v_readlane_b32 s21, v249, 11
	v_readlane_b32 s22, v249, 12
	v_readlane_b32 s23, v249, 13
	s_add_u32 s5, s18, s5
	s_addc_u32 s12, s19, 0
	v_readlane_b32 s20, v248, 31
	v_mov_b32_e32 v208, v188
	v_mov_b32_e32 v18, v188
	s_add_u32 s16, s5, 0x3000000
	v_readlane_b32 s21, v248, 32
	s_addc_u32 s17, s12, 0
	v_ashrrev_i32_e32 v3, 31, v18
	s_mov_b64 s[12:13], s[20:21]
	v_lshrrev_b32_e32 v3, 28, v3
	s_add_u32 s4, s12, s4
	v_ashrrev_i32_e32 v0, 1, v18
	v_add_u32_e32 v3, v18, v3
	s_addc_u32 s5, s13, 0
	s_lshl_b32 s12, s6, 8
	v_and_b32_e32 v0, 0xffffffe0, v0
	v_ashrrev_i32_e32 v176, 4, v3
	v_and_b32_e32 v3, -16, v3
	v_ashrrev_i32_e32 v8, 3, v18
	v_and_b32_e32 v19, 31, v18
	v_add_u32_e32 v20, s12, v0
	v_lshrrev_b32_e32 v0, 2, v18
	v_sub_u32_e32 v21, v18, v3
	v_add_u32_e32 v3, 0x200, v18
	v_ashrrev_i32_e32 v9, 31, v8
	v_or_b32_e32 v2, v20, v19
	v_mov_b64_e32 v[4:5], s[14:15]
	v_and_b32_e32 v160, 8, v0
	v_ashrrev_i32_e32 v6, 31, v3
	v_lshlrev_b64 v[10:11], 13, v[8:9]
	v_lshlrev_b32_e32 v9, 4, v18
	v_mad_i64_i32 v[4:5], s[14:15], v2, s75, v[4:5]
	v_lshlrev_b32_e32 v0, 1, v160
	v_lshrrev_b32_e32 v6, 28, v6
	v_lshl_add_u64 v[10:11], s[16:17], 0, v[10:11]
	v_and_b32_e32 v12, 0x70, v9
	v_mov_b32_e32 v13, v1
	v_lshl_add_u64 v[4:5], v[4:5], 0, v[0:1]
	v_add_u32_e32 v6, v3, v6
	v_lshl_add_u64 v[162:163], v[10:11], 0, v[12:13]
	v_ashrrev_i32_e32 v10, 3, v3
	global_load_dwordx4 v[140:143], v[4:5], off
	global_load_dwordx4 v[136:139], v[4:5], off offset:32
	global_load_dwordx4 v[132:135], v[4:5], off offset:64
	global_load_dwordx4 v[128:131], v[4:5], off offset:96
	global_load_dwordx4 v[124:127], v[4:5], off offset:128
	global_load_dwordx4 v[120:123], v[4:5], off offset:160
	global_load_dwordx4 v[116:119], v[4:5], off offset:192
	global_load_dwordx4 v[112:115], v[4:5], off offset:224
	v_ashrrev_i32_e32 v177, 4, v6
	v_and_b32_e32 v6, -16, v6
	v_ashrrev_i32_e32 v11, 31, v10
	v_sub_u32_e32 v22, v3, v6
	v_lshlrev_b64 v[14:15], 13, v[10:11]
	v_lshlrev_b32_e32 v6, 3, v22
	v_lshl_add_u64 v[14:15], s[16:17], 0, v[14:15]
	v_lshlrev_b32_e32 v4, 3, v21
	v_ashrrev_i32_e32 v7, 31, v6
	v_lshl_add_u64 v[166:167], v[14:15], 0, v[12:13]
	v_mov_b64_e32 v[14:15], s[0:1]
	v_ashrrev_i32_e32 v5, 31, v4
	v_lshlrev_b64 v[6:7], 1, v[6:7]
	v_mad_i64_i32 v[16:17], s[14:15], v177, s75, v[14:15]
	v_lshlrev_b64 v[4:5], 1, v[4:5]
	v_lshl_add_u64 v[16:17], v[16:17], 0, v[6:7]
	v_mad_i64_i32 v[14:15], s[14:15], v176, s75, v[14:15]
	global_load_dwordx4 v[144:147], v[166:167], off
	global_load_dwordx4 v[148:151], v[162:163], off
	v_lshl_add_u64 v[14:15], v[14:15], 0, v[4:5]
	global_load_dwordx4 v[152:155], v[16:17], off
	global_load_dwordx4 v[156:159], v[14:15], off
	v_lshl_add_u64 v[168:169], s[0:1], 0, v[4:5]
	v_lshl_add_u64 v[170:171], s[0:1], 0, v[6:7]
	s_movk_i32 s0, 0x110
	v_lshlrev_b32_e32 v11, 1, v18
	v_lshrrev_b32_e32 v13, 1, v18
	v_add_u32_e32 v174, 64, v0
	v_mul_lo_u32 v0, v176, s0
	v_ashrrev_i32_e32 v3, 31, v2
	v_and_b32_e32 v9, 19, v18
	v_and_b32_e32 v11, 8, v11
	v_and_b32_e32 v13, 4, v13
	v_add_u32_e32 v17, 64, v0
	v_mul_lo_u32 v0, v177, s0
	s_movk_i32 s0, 0x90
	s_add_i32 s13, s12, 0x100
	v_or3_b32 v9, v9, v11, v13
	v_add_u32_e32 v16, 64, v12
	v_or_b32_e32 v179, 31, v20
	v_lshlrev_b64 v[2:3], 9, v[2:3]
	v_lshlrev_b32_e32 v18, 4, v21
	v_add_u32_e32 v20, 64, v0
	v_lshlrev_b32_e32 v21, 4, v22
	v_mul_lo_u32 v22, v8, s0
	v_mul_lo_u32 v23, v10, s0
	v_mov_b32_e32 v14, v1
	v_mov_b32_e32 v15, v1
	s_lshr_b32 s13, s13, 6
	v_lshl_add_u64 v[164:165], s[4:5], 0, v[2:3]
	v_mul_u32_u24_e32 v178, 0x110, v9
	v_mul_u32_u24_e32 v175, 0x90, v19
	v_mov_b32_e32 v0, v1
	v_mov_b32_e32 v2, v1
	v_mov_b32_e32 v3, v1
	v_mov_b32_e32 v4, v1
	v_mov_b32_e32 v5, v1
	v_mov_b32_e32 v6, v1
	v_mov_b32_e32 v7, v1
	v_mov_b32_e32 v8, v1
	v_mov_b32_e32 v9, v1
	v_mov_b32_e32 v10, v1
	v_mov_b32_e32 v11, v1
	v_mov_b32_e32 v12, v1
	v_mov_b32_e32 v13, v1
	v_add_u32_e32 v180, v17, v18
	v_add_u32_e32 v181, v20, v21
	v_add_u32_e32 v182, v16, v22
	v_add_u32_e32 v183, v16, v23
	v_mov_b64_e32 v[30:31], v[14:15]
	v_mov_b64_e32 v[46:47], v[14:15]
	v_mov_b64_e32 v[62:63], v[14:15]
	v_mov_b64_e32 v[78:79], v[14:15]
	s_add_i32 s14, s13, -1
	s_mov_b32 s15, 0
	v_mov_b32_e32 v184, 0xf149f2ca
	v_mov_b32_e32 v161, 0
	s_mov_b32 s0, 64
	v_mov_b64_e32 v[172:173], v[164:165]
	v_mov_b64_e32 v[28:29], v[12:13]
	v_mov_b64_e32 v[26:27], v[10:11]
	v_mov_b64_e32 v[24:25], v[8:9]
	v_mov_b64_e32 v[22:23], v[6:7]
	v_mov_b64_e32 v[20:21], v[4:5]
	v_mov_b64_e32 v[18:19], v[2:3]
	v_mov_b64_e32 v[16:17], v[0:1]
	v_mov_b64_e32 v[44:45], v[12:13]
	v_mov_b64_e32 v[42:43], v[10:11]
	v_mov_b64_e32 v[40:41], v[8:9]
	v_mov_b64_e32 v[38:39], v[6:7]
	v_mov_b64_e32 v[36:37], v[4:5]
	v_mov_b64_e32 v[34:35], v[2:3]
	v_mov_b64_e32 v[32:33], v[0:1]
	v_mov_b64_e32 v[60:61], v[12:13]
	v_mov_b64_e32 v[58:59], v[10:11]
	v_mov_b64_e32 v[56:57], v[8:9]
	v_mov_b64_e32 v[54:55], v[6:7]
	v_mov_b64_e32 v[52:53], v[4:5]
	v_mov_b64_e32 v[50:51], v[2:3]
	v_mov_b64_e32 v[48:49], v[0:1]
	v_mov_b64_e32 v[76:77], v[12:13]
	v_mov_b64_e32 v[74:75], v[10:11]
	v_mov_b64_e32 v[72:73], v[8:9]
	v_mov_b64_e32 v[70:71], v[6:7]
	v_mov_b64_e32 v[68:69], v[4:5]
	v_mov_b64_e32 v[66:67], v[2:3]
	v_mov_b64_e32 v[64:65], v[0:1]
	s_mov_b32 s18, 0xefa18f08
	v_readlane_b32 s22, v248, 33
	v_readlane_b32 s23, v248, 34
	s_branch .LBB0_156

; DI int next_item(u32* ctr0, int idx, int* sh) {
;   asm volatile("" : "+s"(idx));
;   u32* ctr = ctr0 + idx;
;   __syncthreads();
;   if (threadIdx.x == 0) *sh = (int)atomicAdd(ctr, 1u);
;   __syncthreads();
;   return *sh;
; }
; __global__ void __launch_bounds__(NT) fwd_megakernel(Params p) {
;     ...
;       case 3: {
;         for (;;) {
;           const int it = next_item(p.ctr, layer * 8 + 1, &sh_item);
;           if (it >= 256 + 192 + 256 + 256) break;
.LBB0_196:
	s_and_b64 vcc, exec, s[0:1]
	s_cbranch_vccz .LBB0_999
	s_cmp_gt_i32 s61, 1
	s_mov_b64 s[0:1], -1
	s_cbranch_scc0 .LBB0_969
	s_cmp_gt_i32 s61, 2
	s_cbranch_scc0 .LBB0_274
	v_readlane_b32 s0, v250, 28
	s_mov_b32 s20, s0
	s_lshl_b32 s0, s0, 3
	v_readlane_b32 s1, v250, 29
	v_writelane_b32 v250, s0, 34
	s_or_b32 s80, s0, 1
	s_lshl_b32 s0, s20, 8
	s_ashr_i32 s1, s0, 31
	v_readlane_b32 s4, v249, 31
	s_lshl_b64 s[0:1], s[0:1], 2
	v_readlane_b32 s12, v249, 39
	v_readlane_b32 s13, v249, 40
	s_add_u32 s81, s12, s0
	s_addc_u32 s82, s13, s1
	s_ashr_i32 s21, s20, 31
	s_lshl_b64 s[0:1], s[20:21], 2
	v_readlane_b32 s2, v248, 0
	v_readlane_b32 s3, v248, 1
	s_add_u32 s36, s2, s0
	s_mov_b32 s0, s20
	s_addc_u32 s37, s3, s1
	v_writelane_b32 v250, s0, 28
	v_readlane_b32 s14, v249, 41
	v_readlane_b32 s15, v249, 42
	v_writelane_b32 v250, s1, 29
	s_lshl_b32 s0, s20, 7
	s_ashr_i32 s1, s0, 31
	v_writelane_b32 v250, s60, 35
	s_lshl_b64 s[0:1], s[0:1], 2
	v_writelane_b32 v250, s61, 36
	s_add_u32 s72, s14, s0
	v_writelane_b32 v250, s36, 37
	s_addc_u32 s73, s15, s1
	v_readlane_b32 s5, v249, 32
	v_writelane_b32 v250, s37, 38
	v_readlane_b32 s6, v249, 33
	v_readlane_b32 s7, v249, 34
	v_readlane_b32 s8, v249, 35
	v_readlane_b32 s9, v249, 36
	v_readlane_b32 s10, v249, 37
	v_readlane_b32 s11, v249, 38
	v_readlane_b32 s16, v249, 43
	v_readlane_b32 s17, v249, 44
	v_readlane_b32 s18, v249, 45
	v_readlane_b32 s19, v249, 46
	s_branch .Lq_first_1
.Lq_first_1:
	s_mov_b32 s0, s80
	s_waitcnt vmcnt(0) lgkmcnt(0)
	s_barrier
	s_mov_b64 s[2:3], exec
	v_readlane_b32 s4, v248, 2
	v_readlane_b32 s5, v248, 3
	s_and_b64 s[4:5], s[2:3], s[4:5]
	s_mov_b64 exec, s[4:5]
	s_cbranch_execz .LBB0_206
	s_ashr_i32 s1, s0, 31
	v_lshl_add_u64 v[2:3], s[0:1], 2, v[190:191]
	global_atomic_add v0, v[2:3], v209, off sc0
	s_waitcnt vmcnt(0)
	ds_write_b32 v1, v0 offset:48
.LBB0_206:
	s_or_b64 exec, exec, s[2:3]
	s_waitcnt lgkmcnt(0)
	s_barrier
	s_branch .Lq_common_1

; DI int opq(int x) { asm volatile("" : "+v"(x)); return x; }
; DI f32x16 zero16() { f32x16 z; for (int i = 0; i < 16; ++i) z[i] = 0.f; return z; }
; DI long vt_off(int grp, int b, int head) { return ((long)((grp * BATCH + b) * 4 + head)) * 128 * SEQ; }
; template <int DQK, int MODE>
; DI void attn_core(const u16* __restrict__ Qg, int ldq, const u16* __restrict__ Kg, int ldk, const u16* __restrict__ Vtg,
;                   const u64* __restrict__ maskg, int q0, float scale, char* smem, int* sflags, f32x16 (&o)[4], float& l_run) {
;     ...
;   const int tid = opq(threadIdx.x), lane = tid & 63, wid = tid >> 6, l31 = lane & 31, hh = lane >> 5;
;   const int qrow = q0 + 32 * wid + l31;
;   bf16x8 qf[NKS];
; #pragma unroll
;   for (int ks = 0; ks < NKS; ++ks) qf[ks] = *(const bf16x8*)(Qg + (long)qrow * ldq + ks * 16 + hh * 8);
;   o[0] = zero16(); o[1] = zero16(); o[2] = zero16(); o[3] = zero16();
;   float m_run = -1e30f, r_run = 0.f;
;   l_run = 0.f;
;   const int ntiles = (q0 + 256) >> 6;
;   const int step = (MODE == 2) ? -1 : 1;
;   int tau = (MODE == 2) ? ntiles - 1 : 0;
; __global__ void __launch_bounds__(NT) fwd_megakernel(Params p) {
;     ...
;           } else {
;             const int t = it - 704;
;             const int qt = 15 - (t >> 4), bh = t & 15, b = bh >> 2, head = bh & 3;
;             const u16* base = p.PROJ + (long)b * SEQ * PW;
;     ...
;             attn_item_simple<128, 2>(p, base + CQ + head * 128, PW, base + CK + head * 128, PW, p.VT + vt_off(2, b, head), nullptr,
;                                      b, qt * 256, 0.08838834764831845f, 1024 + head * 128, smem, sflags);
.LBB0_204:
	s_mov_b32 s0, s80
	s_mov_b64 s[2:3], exec
	v_readlane_b32 s4, v248, 2
	v_readlane_b32 s5, v248, 3
	s_and_b64 s[4:5], s[2:3], s[4:5]
	s_mov_b64 exec, s[4:5]
	s_cbranch_execz .Lq_skip_1
	s_ashr_i32 s1, s0, 31
	v_lshl_add_u64 v[2:3], s[0:1], 2, v[190:191]
	global_atomic_add v0, v[2:3], v209, off sc0
	s_waitcnt vmcnt(0)
	ds_write_b32 v1, v0 offset:48
.Lq_skip_1:
	s_or_b64 exec, exec, s[2:3]
	s_waitcnt vmcnt(0) lgkmcnt(0)
	s_barrier
.Lq_common_1:
	ds_read_b32 v0, v1 offset:48
	s_movk_i32 s0, 0x3bf
	s_waitcnt lgkmcnt(0)
	v_cmp_lt_i32_e32 vcc, s0, v0
	v_readfirstlane_b32 s83, v0
	s_mov_b64 s[0:1], -1
	s_cbranch_vccnz .LBB0_203
	s_cmpk_gt_i32 s83, 0xff
	s_cbranch_scc0 .LBB0_236
	s_cmpk_gt_u32 s83, 0x1bf
	s_cbranch_scc0 .LBB0_231
	s_cmpk_gt_u32 s83, 0x2bf
	s_cbranch_scc0 .LBB0_225
	s_bfe_u32 s85, s83, 0x20002
	s_mul_i32 s0, s85, 0x2600000
	v_readlane_b32 s4, v249, 6
	v_readlane_b32 s5, v249, 7
	s_add_u32 s0, s4, s0
	s_addc_u32 s1, s5, 0
	s_lshl_b32 s2, s83, 7
	s_and_b32 s84, s2, 0x180
	s_lshl_b32 s2, s84, 1
	s_add_u32 s0, s0, s2
	v_readlane_b32 s6, v249, 8
	s_addc_u32 s1, s1, 0
	s_lshl_b32 s2, s83, 4
	s_and_b32 s6, s2, 0x7fffff00
	v_mov_b32_e32 v180, v188
	v_mov_b32_e32 v10, v188
	s_sub_i32 s86, 0x3b00, s6
	v_mov_b64_e32 v[2:3], s[0:1]
	v_ashrrev_i32_e32 v12, 6, v10
	v_and_b32_e32 v13, 31, v10
	v_lshl_add_u32 v181, v12, 5, s86
	v_bfe_u32 v0, v10, 5, 1
	v_or_b32_e32 v130, v181, v13
	v_mad_i64_i32 v[2:3], s[2:3], v130, s75, v[2:3]
	v_lshlrev_b32_e32 v14, 3, v0
	v_lshlrev_b32_e32 v0, 4, v0
	v_lshl_add_u64 v[2:3], v[2:3], 0, v[0:1]
	global_load_dwordx4 v[98:101], v[2:3], off offset:2048
	global_load_dwordx4 v[102:105], v[2:3], off offset:2080
	global_load_dwordx4 v[106:109], v[2:3], off offset:2112
	global_load_dwordx4 v[110:113], v[2:3], off offset:2144
	global_load_dwordx4 v[114:117], v[2:3], off offset:2176
	global_load_dwordx4 v[118:121], v[2:3], off offset:2208
	global_load_dwordx4 v[122:125], v[2:3], off offset:2240
	global_load_dwordx4 v[126:129], v[2:3], off offset:2272
	v_lshlrev_b32_e32 v3, 1, v10
	v_lshrrev_b32_e32 v4, 1, v10
	v_and_b32_e32 v2, 19, v10
	v_and_b32_e32 v3, 8, v3
	v_and_b32_e32 v4, 4, v4
	v_or3_b32 v15, v2, v3, v4
	v_ashrrev_i32_e32 v2, 31, v10
	v_lshrrev_b32_e32 v2, 28, v2
	v_add_u32_e32 v2, v10, v2
	v_ashrrev_i32_e32 v16, 4, v2
	v_and_b32_e32 v2, -16, v2
	v_sub_u32_e32 v17, v10, v2
	v_lshlrev_b32_e32 v2, 3, v17
	v_ashrrev_i32_e32 v3, 31, v2
	v_add_u32_e32 v6, 0x200, v10
	v_lshl_add_u64 v[132:133], v[2:3], 1, s[0:1]
	v_ashrrev_i32_e32 v2, 31, v6
	v_lshrrev_b32_e32 v2, 28, v2
	v_add_u32_e32 v2, v6, v2
	v_ashrrev_i32_e32 v18, 4, v2
	v_and_b32_e32 v2, -16, v2
	v_sub_u32_e32 v19, v6, v2
	v_lshlrev_b32_e32 v2, 3, v19
	s_movk_i32 s4, 0x110
	v_readlane_b32 s8, v249, 10
	v_readlane_b32 s9, v249, 11
	v_ashrrev_i32_e32 v3, 31, v2
	v_add_u32_e32 v21, 64, v0
	v_mul_lo_u32 v0, v16, s4
	v_lshl_add_u64 v[134:135], v[2:3], 1, s[0:1]
	v_ashrrev_i32_e32 v2, 3, v10
	v_ashrrev_i32_e32 v6, 3, v6
	v_add_u32_e32 v22, 64, v0
	v_mul_lo_u32 v0, v18, s4
	s_movk_i32 s4, 0x90
	s_sub_i32 s74, 0, s6
	v_readlane_b32 s8, v249, 29
	v_readlane_b32 s7, v249, 9
	v_readlane_b32 s10, v249, 12
	v_readlane_b32 s11, v249, 13
	s_sub_i32 s2, 0x3c00, s6
	v_ashrrev_i32_e32 v3, 31, v2
	v_mul_lo_u32 v24, v2, s4
	v_mul_lo_u32 v25, v6, s4
	s_and_b32 s4, s83, 15
	v_readlane_b32 s9, v249, 30
	s_ashr_i32 s75, s74, 31
	s_lshr_b32 s7, s2, 6
	v_lshlrev_b64 v[4:5], 13, v[2:3]
	v_ashrrev_i32_e32 v7, 31, v6
	v_lshlrev_b32_e32 v3, 4, v10
	s_mov_b32 s11, s9
	s_lshl_b32 s10, s4, 20
	s_lshl_b64 s[4:5], s[74:75], 1
	v_readlane_b32 s8, v248, 61
	v_lshlrev_b64 v[8:9], 13, v[6:7]
	v_and_b32_e32 v7, 0x70, v3
	v_lshl_add_u64 v[2:3], s[10:11], 0, v[4:5]
	s_add_u32 s4, s8, s4
	v_readlane_b32 s8, v248, 62
	v_or_b32_e32 v2, v2, v7
	s_addc_u32 s5, s8, s5
	v_add_u32_e32 v23, 64, v0
	v_lshl_add_u64 v[136:137], s[4:5], 0, v[2:3]
	v_lshl_add_u64 v[2:3], s[10:11], 0, v[8:9]
	v_subrev_u32_e32 v0, s6, v18
	v_and_b32_e32 v11, 63, v10
	v_add_u32_e32 v20, 64, v7
	v_lshlrev_b32_e32 v17, 4, v17
	v_lshlrev_b32_e32 v19, 4, v19
	v_mul_u32_u24_e32 v26, 0x110, v15
	v_mul_u32_u24_e32 v27, 0x90, v13
	v_subrev_u32_e32 v184, s6, v14
	v_or_b32_e32 v2, v2, v7
	v_add_u32_e32 v185, 0x3bc0, v0
	v_subrev_u32_e32 v0, s6, v16
	v_mov_b32_e32 v14, v1
	v_mov_b32_e32 v15, v1
	v_cmp_gt_u32_e64 s[0:1], 32, v11
	v_cmp_eq_u32_e64 s[2:3], 0, v11
	v_lshlrev_b32_e32 v183, 2, v12
	v_lshl_add_u64 v[138:139], s[4:5], 0, v[2:3]
	v_add_u32_e32 v186, 0x3bc0, v0
	v_mov_b32_e32 v0, v1
	v_mov_b32_e32 v2, v1
	v_mov_b32_e32 v3, v1
	v_mov_b32_e32 v4, v1
	v_mov_b32_e32 v5, v1
	v_mov_b32_e32 v6, v1
	v_mov_b32_e32 v7, v1
	v_mov_b32_e32 v8, v1
	v_mov_b32_e32 v9, v1
	v_mov_b32_e32 v10, v1
	v_mov_b32_e32 v11, v1
	v_mov_b32_e32 v12, v1
	v_mov_b32_e32 v13, v1
	v_add_u32_e32 v187, v22, v17
	v_add_u32_e32 v206, v23, v19
	v_add_u32_e32 v207, v20, v24
	v_add_u32_e32 v208, v20, v25
	v_add_u32_e32 v210, v21, v26
	v_add_u32_e32 v211, v21, v27
	v_mov_b64_e32 v[32:33], v[14:15]
	v_mov_b64_e32 v[48:49], v[14:15]
	v_mov_b64_e32 v[64:65], v[14:15]
	s_sub_i32 s4, 0, s7
	v_mov_b64_e32 v[30:31], v[12:13]
	v_mov_b64_e32 v[28:29], v[10:11]
	v_mov_b64_e32 v[26:27], v[8:9]
	v_mov_b64_e32 v[24:25], v[6:7]
	v_mov_b64_e32 v[22:23], v[4:5]
	v_mov_b64_e32 v[20:21], v[2:3]
	v_mov_b64_e32 v[18:19], v[0:1]
	v_mov_b64_e32 v[46:47], v[12:13]
	v_mov_b64_e32 v[44:45], v[10:11]
	v_mov_b64_e32 v[42:43], v[8:9]
	v_mov_b64_e32 v[40:41], v[6:7]
	v_mov_b64_e32 v[38:39], v[4:5]
	v_mov_b64_e32 v[36:37], v[2:3]
	v_mov_b64_e32 v[34:35], v[0:1]
	v_mov_b64_e32 v[62:63], v[12:13]
	v_mov_b64_e32 v[60:61], v[10:11]
	v_mov_b64_e32 v[58:59], v[8:9]
	v_mov_b64_e32 v[56:57], v[6:7]
	v_mov_b64_e32 v[54:55], v[4:5]
	v_mov_b64_e32 v[52:53], v[2:3]
	v_mov_b64_e32 v[50:51], v[0:1]
	v_mov_b64_e32 v[16:17], v[14:15]
	s_mov_b32 s90, s62
	v_or_b32_e32 v182, 31, v181
	s_mov_b32 s87, 0
	v_mov_b32_e32 v131, v130
	s_movk_i32 s75, 0x2600
	s_mov_b32 s71, s9
	v_mov_b32_e32 v141, 0
	v_mov_b32_e32 v212, s4
	v_mov_b64_e32 v[14:15], v[12:13]
	v_mov_b64_e32 v[12:13], v[10:11]
	v_mov_b64_e32 v[10:11], v[8:9]
	v_mov_b64_e32 v[8:9], v[6:7]
	v_mov_b64_e32 v[6:7], v[4:5]
	v_mov_b64_e32 v[4:5], v[2:3]
	v_mov_b64_e32 v[2:3], v[0:1]
	s_branch .LBB0_212

; DI int next_item(u32* ctr0, int idx, int* sh) {
;   asm volatile("" : "+s"(idx));
;   u32* ctr = ctr0 + idx;
;   __syncthreads();
;   if (threadIdx.x == 0) *sh = (int)atomicAdd(ctr, 1u);
;   __syncthreads();
;   return *sh;
; }
; __global__ void __launch_bounds__(NT) fwd_megakernel(Params p) {
;     ...
;           for (;;) {
;             const int it = next_item(p.ctr, layer * 8 + 0, &sh_item);
;             if (it >= 1024) break;
.LBB0_310:
	v_readlane_b32 s0, v250, 34
	s_mov_b64 s[2:3], exec
	v_readlane_b32 s4, v248, 2
	v_readlane_b32 s5, v248, 3
	s_and_b64 s[4:5], s[2:3], s[4:5]
	s_mov_b64 exec, s[4:5]
	s_cbranch_execz .Lq_skip_2
	s_ashr_i32 s1, s0, 31
	v_lshl_add_u64 v[2:3], s[0:1], 2, v[190:191]
	global_atomic_add v0, v[2:3], v209, off sc0
	s_waitcnt vmcnt(0)
	ds_write_b32 v1, v0 offset:48

; DI int opq(int x) { asm volatile("" : "+v"(x)); return x; }
; DI void indexer_item(const Params& p, int b, int qt16, char* smem) {
;   u16* iqs = (u16*)smem;
;   float* wls = (float*)(smem + 16 * 2080);
;   const int tid = opq(threadIdx.x), lane = tid & 63, wid = tid >> 6, l15 = lane & 15, g4 = lane >> 4;
;   const int t0 = qt16 * 16;
;   const u16* base = p.PROJ + (long)b * SEQ * PW;
;   float* scr = p.SCR + (long)blockIdx.x * 16 * SEQ;
; #pragma unroll
;   for (int i = 0; i < 4; ++i) {
;     const int v = tid + NT * i, q = v >> 7, c = v & 127;
;     *(u32x4*)(iqs + q * 1040 + c * 8) = *(const u32x4*)(base + (long)(t0 + q) * PW + DIQ + c * 8);
;   }
;   if (tid < 256) {
;     const int q = tid >> 4, h = tid & 15;
;     wls[tid] = __uint_as_float(((u32)base[(long)(t0 + q) * PW + DIW + h]) << 16);
;   }
; __global__ void __launch_bounds__(NT) fwd_megakernel(Params p) {
;     ...
;             const int it = next_item(p.ctr, layer * 8 + 0, &sh_item);
;             if (it >= 1024) break;
;     ...
;             indexer_item(p, it & 3, 255 - (it >> 2), smem);
.Lq_common_2:
	ds_read_b32 v0, v1 offset:48
	s_movk_i32 s0, 0x3ff
	s_waitcnt lgkmcnt(0)
	v_cmp_lt_i32_e32 vcc, s0, v0
	s_mov_b64 s[0:1], -1
	s_cbranch_vccnz .LBB0_309
	v_lshlrev_b32_e32 v2, 2, v0
	v_lshlrev_b32_e32 v0, 12, v0
	v_mov_b32_e32 v34, v188
	v_and_b32_e32 v2, -16, v2
	v_and_b32_e32 v86, 0x3000, v0
	v_readlane_b32 s0, v249, 6
	s_waitcnt vmcnt(23)
	v_sub_u32_e32 v99, 0xff0, v2
	v_mul_lo_u32 v0, v86, s75
	v_readlane_b32 s1, v249, 7
	v_ashrrev_i32_e32 v3, 7, v34
	v_add_u32_e32 v4, v3, v99
	v_lshl_add_u64 v[88:89], s[0:1], 0, v[0:1]
	v_lshlrev_b32_e32 v0, 4, v34
	v_readlane_b32 s2, v249, 8
	v_and_b32_e32 v0, 0x7f0, v0
	v_mad_i64_i32 v[4:5], s[0:1], v4, s75, v[88:89]
	v_lshl_add_u64 v[4:5], v[4:5], 0, v[0:1]
	s_movk_i32 s2, 0x1000
	v_add_co_u32_e32 v4, vcc, s2, v4
	v_readlane_b32 s3, v249, 9
	s_nop 0
	v_addc_co_u32_e32 v5, vcc, 0, v5, vcc
	global_load_dwordx4 v[4:7], v[4:5], off offset:2048
	v_add_u32_e32 v8, 64, v0
	s_movk_i32 s3, 0x820
	v_mad_u64_u32 v[10:11], s[0:1], v3, s3, v[8:9]
	v_add_u32_e32 v3, 0x200, v34
	v_ashrrev_i32_e32 v3, 7, v3
	v_and_b32_e32 v87, 15, v34
	v_readlane_b32 s4, v249, 10
	v_readlane_b32 s5, v249, 11
	v_readlane_b32 s6, v249, 12
	v_readlane_b32 s7, v249, 13
	s_waitcnt vmcnt(0)
	ds_write_b128 v10, v[4:7]
	v_add_u32_e32 v4, v3, v99
	v_mad_i64_i32 v[4:5], s[0:1], v4, s75, v[88:89]
	v_lshl_add_u64 v[4:5], v[4:5], 0, v[0:1]
	v_add_co_u32_e32 v4, vcc, s2, v4
	v_mad_u64_u32 v[10:11], s[0:1], v3, s3, v[8:9]
	s_nop 0
	v_addc_co_u32_e32 v5, vcc, 0, v5, vcc
	global_load_dwordx4 v[4:7], v[4:5], off offset:2048
	v_add_u32_e32 v3, 0x400, v34
	v_ashrrev_i32_e32 v3, 7, v3
	s_waitcnt vmcnt(0)
	ds_write_b128 v10, v[4:7]
	v_add_u32_e32 v4, v3, v99
	v_mad_i64_i32 v[4:5], s[0:1], v4, s75, v[88:89]
	v_lshl_add_u64 v[4:5], v[4:5], 0, v[0:1]
	v_add_co_u32_e32 v4, vcc, s2, v4
	v_mad_u64_u32 v[10:11], s[0:1], v3, s3, v[8:9]
	s_nop 0
	v_addc_co_u32_e32 v5, vcc, 0, v5, vcc
	global_load_dwordx4 v[4:7], v[4:5], off offset:2048
	v_add_u32_e32 v3, 0x600, v34
	v_ashrrev_i32_e32 v3, 7, v3
	v_mad_u64_u32 v[8:9], s[0:1], v3, s3, v[8:9]
	s_waitcnt vmcnt(0)
	ds_write_b128 v10, v[4:7]
	v_add_u32_e32 v4, v3, v99
	v_mad_i64_i32 v[4:5], s[0:1], v4, s75, v[88:89]
	v_lshl_add_u64 v[4:5], v[4:5], 0, v[0:1]
	v_add_co_u32_e32 v4, vcc, 0x1000, v4
	s_movk_i32 s0, 0x100
	s_nop 0
	v_addc_co_u32_e32 v5, vcc, 0, v5, vcc
	global_load_dwordx4 v[4:7], v[4:5], off offset:2048
	v_cmp_gt_i32_e32 vcc, s0, v34
	s_waitcnt vmcnt(0)
	ds_write_b128 v8, v[4:7]
	s_and_saveexec_b64 s[0:1], vcc
	s_cbranch_execz .LBB0_315
	v_ashrrev_i32_e32 v0, 4, v34
	v_add_u32_e32 v0, v0, v99
	v_mad_i64_i32 v[4:5], s[2:3], v0, s75, v[88:89]
	v_lshlrev_b32_e32 v0, 1, v87
	v_lshl_add_u64 v[4:5], v[4:5], 0, v[0:1]
	v_add_co_u32_e32 v4, vcc, 0x2000, v4
	v_lshl_add_u32 v3, v34, 2, 64
	s_nop 0
	v_addc_co_u32_e32 v5, vcc, 0, v5, vcc
	global_load_ushort v0, v[4:5], off offset:1408
	s_waitcnt vmcnt(0)
	v_lshlrev_b32_e32 v0, 16, v0
	ds_write_b32 v3, v0 offset:33280
